# v56 + sc0 on the FF1 K-loop LDS-DMA tile loads
# baseline (speedup 1.0000x reference)
.LBB0_211:
	s_add_i32 s73, s58, 2
	s_add_u32 s74, s56, 0x80
	s_addc_u32 s59, s57, 0
	s_add_i32 s78, 0, 0x10000
	s_cmp_eq_u32 s63, s58
	s_cselect_b32 s59, s51, s59
	s_cselect_b32 s58, s55, s74
	v_add_u32_e32 v0, s78, v146
	s_cselect_b32 s75, s45, s72
	s_cselect_b32 s74, s44, s67
	s_add_i32 s80, 0, 0x14000
	ds_read_b128 v[148:151], v0
	ds_read_b128 v[152:155], v0 offset:1024
	ds_read_b128 v[156:159], v0 offset:2048
	ds_read_b128 v[160:163], v0 offset:3072
	v_add_u32_e32 v0, s80, v146
	ds_read_b128 v[164:167], v0
	ds_read_b128 v[168:171], v0 offset:1024
	ds_read_b128 v[172:175], v0 offset:2048
	ds_read_b128 v[176:179], v0 offset:3072
	s_mov_b32 m0, s31
	v_lshl_add_u64 v[142:143], s[56:57], 0, v[136:137]
	global_load_lds_dwordx4 v[142:143], off sc0
	v_lshl_add_u64 v[142:143], s[56:57], 0, v[132:133]
	s_mov_b32 m0, s53
	s_nop 0
	global_load_lds_dwordx4 v[142:143], off sc0
	v_lshl_add_u64 v[142:143], s[56:57], 0, v[138:139]
	s_add_i32 m0, s27, 0xc000
	s_nop 0
	global_load_lds_dwordx4 v[142:143], off sc0
	v_lshl_add_u64 v[142:143], s[56:57], 0, v[140:141]
	s_add_i32 m0, s27, 0xe000
	s_nop 0
	global_load_lds_dwordx4 v[142:143], off sc0
	ds_read_b128 v[180:183], v147
	ds_read_b128 v[184:187], v147 offset:1024
	ds_read_b128 v[200:203], v147 offset:2048
	ds_read_b128 v[204:207], v147 offset:3072
	ds_read_b128 v[208:211], v147 offset:4096
	ds_read_b128 v[212:215], v147 offset:5120
	ds_read_b128 v[216:219], v147 offset:6144
	ds_read_b128 v[220:223], v147 offset:7168
	s_waitcnt vmcnt(8)
	s_waitcnt lgkmcnt(0)
	s_barrier
	s_setprio 1
	s_waitcnt lgkmcnt(0)
	v_mfma_f32_16x16x32_bf16 v[122:125], v[148:151], v[180:183], v[122:125]
	v_mfma_f32_16x16x32_bf16 v[126:129], v[156:159], v[180:183], v[126:129]
	v_mfma_f32_16x16x32_bf16 v[110:113], v[148:151], v[200:203], v[110:113]
	v_mfma_f32_16x16x32_bf16 v[106:109], v[156:159], v[200:203], v[106:109]
	v_mfma_f32_16x16x32_bf16 v[94:97], v[148:151], v[208:211], v[94:97]
	v_mfma_f32_16x16x32_bf16 v[90:93], v[156:159], v[208:211], v[90:93]
	v_mfma_f32_16x16x32_bf16 v[78:81], v[148:151], v[216:219], v[78:81]
	v_mfma_f32_16x16x32_bf16 v[74:77], v[156:159], v[216:219], v[74:77]
	v_mfma_f32_16x16x32_bf16 v[122:125], v[152:155], v[184:187], v[122:125]
	v_mfma_f32_16x16x32_bf16 v[126:129], v[160:163], v[184:187], v[126:129]
	v_mfma_f32_16x16x32_bf16 v[110:113], v[152:155], v[204:207], v[110:113]
	v_mfma_f32_16x16x32_bf16 v[106:109], v[160:163], v[204:207], v[106:109]
	v_mfma_f32_16x16x32_bf16 v[94:97], v[152:155], v[212:215], v[94:97]
	v_mfma_f32_16x16x32_bf16 v[90:93], v[160:163], v[212:215], v[90:93]
	v_mfma_f32_16x16x32_bf16 v[78:81], v[152:155], v[220:223], v[78:81]
	v_mfma_f32_16x16x32_bf16 v[74:77], v[160:163], v[220:223], v[74:77]
	s_setprio 0
	s_setprio 1
	v_mfma_f32_16x16x32_bf16 v[118:121], v[164:167], v[180:183], v[118:121]
	v_mfma_f32_16x16x32_bf16 v[114:117], v[172:175], v[180:183], v[114:117]
	v_mfma_f32_16x16x32_bf16 v[102:105], v[164:167], v[200:203], v[102:105]
	v_mfma_f32_16x16x32_bf16 v[98:101], v[172:175], v[200:203], v[98:101]
	v_mfma_f32_16x16x32_bf16 v[86:89], v[164:167], v[208:211], v[86:89]
	v_mfma_f32_16x16x32_bf16 v[82:85], v[172:175], v[208:211], v[82:85]
	v_mfma_f32_16x16x32_bf16 v[70:73], v[164:167], v[216:219], v[70:73]
	v_mfma_f32_16x16x32_bf16 v[66:69], v[172:175], v[216:219], v[66:69]
	v_mfma_f32_16x16x32_bf16 v[118:121], v[168:171], v[184:187], v[118:121]
	v_mfma_f32_16x16x32_bf16 v[114:117], v[176:179], v[184:187], v[114:117]
	v_mfma_f32_16x16x32_bf16 v[102:105], v[168:171], v[204:207], v[102:105]
	v_mfma_f32_16x16x32_bf16 v[98:101], v[176:179], v[204:207], v[98:101]
	v_mfma_f32_16x16x32_bf16 v[86:89], v[168:171], v[212:215], v[86:89]
	v_mfma_f32_16x16x32_bf16 v[82:85], v[176:179], v[212:215], v[82:85]
	v_mfma_f32_16x16x32_bf16 v[70:73], v[168:171], v[220:223], v[70:73]
	v_mfma_f32_16x16x32_bf16 v[66:69], v[176:179], v[220:223], v[66:69]
	s_setprio 0
	s_barrier
	s_add_i32 s78, s78, s5
	v_lshl_add_u64 v[142:143], s[74:75], 0, v[134:135]
	s_mov_b32 m0, s78
	ds_read_b128 v[180:183], v147 offset:16384
	ds_read_b128 v[184:187], v147 offset:17408
	ds_read_b128 v[200:203], v147 offset:18432
	ds_read_b128 v[204:207], v147 offset:19456
	ds_read_b128 v[208:211], v147 offset:20480
	ds_read_b128 v[212:215], v147 offset:21504
	ds_read_b128 v[216:219], v147 offset:22528
	ds_read_b128 v[220:223], v147 offset:23552
	global_load_lds_dwordx4 v[142:143], off sc0
	s_add_i32 m0, s78, 0x2000
	v_lshl_add_u64 v[188:189], s[74:75], 0, v[130:131]
	s_add_u32 s74, s74, s6
	s_addc_u32 s75, s75, s7
	s_add_i32 s78, s80, s5
	global_load_lds_dwordx4 v[188:189], off sc0
	v_lshl_add_u64 v[224:225], s[74:75], 0, v[134:135]
	s_mov_b32 m0, s78
	v_lshl_add_u64 v[226:227], s[74:75], 0, v[130:131]
	global_load_lds_dwordx4 v[224:225], off sc0
	s_add_i32 m0, s78, 0x2000
	v_lshl_add_u64 v[228:229], s[58:59], 0, v[136:137]
	global_load_lds_dwordx4 v[226:227], off sc0
	v_lshl_add_u64 v[230:231], s[58:59], 0, v[132:133]
	s_waitcnt vmcnt(6)
	s_waitcnt lgkmcnt(0)
	s_barrier
	s_setprio 1
	s_waitcnt lgkmcnt(0)
	v_mfma_f32_16x16x32_bf16 v[62:65], v[148:151], v[180:183], v[62:65]
	v_mfma_f32_16x16x32_bf16 v[58:61], v[156:159], v[180:183], v[58:61]
	v_mfma_f32_16x16x32_bf16 v[46:49], v[148:151], v[200:203], v[46:49]
	v_mfma_f32_16x16x32_bf16 v[42:45], v[156:159], v[200:203], v[42:45]
	v_mfma_f32_16x16x32_bf16 v[30:33], v[148:151], v[208:211], v[30:33]
	v_mfma_f32_16x16x32_bf16 v[26:29], v[156:159], v[208:211], v[26:29]
	v_mfma_f32_16x16x32_bf16 v[14:17], v[148:151], v[216:219], v[14:17]
	v_mfma_f32_16x16x32_bf16 v[10:13], v[156:159], v[216:219], v[10:13]
	v_mfma_f32_16x16x32_bf16 v[62:65], v[152:155], v[184:187], v[62:65]
	v_mfma_f32_16x16x32_bf16 v[58:61], v[160:163], v[184:187], v[58:61]
	v_mfma_f32_16x16x32_bf16 v[46:49], v[152:155], v[204:207], v[46:49]
	v_mfma_f32_16x16x32_bf16 v[42:45], v[160:163], v[204:207], v[42:45]
	v_mfma_f32_16x16x32_bf16 v[30:33], v[152:155], v[212:215], v[30:33]
	v_mfma_f32_16x16x32_bf16 v[26:29], v[160:163], v[212:215], v[26:29]
	v_mfma_f32_16x16x32_bf16 v[14:17], v[152:155], v[220:223], v[14:17]
	v_mfma_f32_16x16x32_bf16 v[10:13], v[160:163], v[220:223], v[10:13]
	s_setprio 0
	s_setprio 1
	v_mfma_f32_16x16x32_bf16 v[54:57], v[164:167], v[180:183], v[54:57]
	v_mfma_f32_16x16x32_bf16 v[50:53], v[172:175], v[180:183], v[50:53]
	v_mfma_f32_16x16x32_bf16 v[38:41], v[164:167], v[200:203], v[38:41]
	v_mfma_f32_16x16x32_bf16 v[34:37], v[172:175], v[200:203], v[34:37]
	v_mfma_f32_16x16x32_bf16 v[22:25], v[164:167], v[208:211], v[22:25]
	v_mfma_f32_16x16x32_bf16 v[18:21], v[172:175], v[208:211], v[18:21]
	v_mfma_f32_16x16x32_bf16 v[6:9], v[164:167], v[216:219], v[6:9]
	v_mfma_f32_16x16x32_bf16 v[2:5], v[172:175], v[216:219], v[2:5]
	v_mfma_f32_16x16x32_bf16 v[54:57], v[168:171], v[184:187], v[54:57]
	v_mfma_f32_16x16x32_bf16 v[50:53], v[176:179], v[184:187], v[50:53]
	v_mfma_f32_16x16x32_bf16 v[38:41], v[168:171], v[204:207], v[38:41]
	v_mfma_f32_16x16x32_bf16 v[34:37], v[176:179], v[204:207], v[34:37]
	v_mfma_f32_16x16x32_bf16 v[22:25], v[168:171], v[212:215], v[22:25]
	v_mfma_f32_16x16x32_bf16 v[18:21], v[176:179], v[212:215], v[18:21]
	v_mfma_f32_16x16x32_bf16 v[6:9], v[168:171], v[220:223], v[6:9]
	v_mfma_f32_16x16x32_bf16 v[2:5], v[176:179], v[220:223], v[2:5]
	s_setprio 0
	s_barrier
	s_add_i32 s74, 0, 0x18000
	v_add_u32_e32 v0, s74, v146
	s_add_i32 s75, 0, 0x1c000
	ds_read_b128 v[148:151], v0
	ds_read_b128 v[152:155], v0 offset:1024
	ds_read_b128 v[156:159], v0 offset:2048
	ds_read_b128 v[160:163], v0 offset:3072
	v_add_u32_e32 v0, s75, v146
	ds_read_b128 v[164:167], v0
	ds_read_b128 v[168:171], v0 offset:1024
	ds_read_b128 v[172:175], v0 offset:2048
	ds_read_b128 v[176:179], v0 offset:3072
	s_add_u32 s58, s58, s2
	s_addc_u32 s59, s59, s3
	s_mov_b32 m0, s27
	v_lshl_add_u64 v[232:233], s[58:59], 0, v[136:137]
	s_nop 0
	global_load_lds_dwordx4 v[228:229], off sc0
	s_mov_b32 m0, s28
	s_nop 0
	global_load_lds_dwordx4 v[230:231], off sc0
	s_mov_b32 m0, s29
	s_nop 0
	global_load_lds_dwordx4 v[232:233], off sc0
	v_lshl_add_u64 v[232:233], s[58:59], 0, v[132:133]
	s_mov_b32 m0, s30
	s_nop 0
	global_load_lds_dwordx4 v[232:233], off sc0
	ds_read_b128 v[180:183], v147 offset:32768
	ds_read_b128 v[184:187], v147 offset:33792
	ds_read_b128 v[200:203], v147 offset:34816
	ds_read_b128 v[204:207], v147 offset:35840
	ds_read_b128 v[208:211], v147 offset:36864
	ds_read_b128 v[212:215], v147 offset:37888
	ds_read_b128 v[216:219], v147 offset:38912
	ds_read_b128 v[220:223], v147 offset:39936
	s_waitcnt vmcnt(8)
	s_waitcnt lgkmcnt(0)
	s_barrier
	s_setprio 1
	s_waitcnt lgkmcnt(0)
	v_mfma_f32_16x16x32_bf16 v[122:125], v[148:151], v[180:183], v[122:125]
	v_mfma_f32_16x16x32_bf16 v[126:129], v[156:159], v[180:183], v[126:129]
	v_mfma_f32_16x16x32_bf16 v[110:113], v[148:151], v[200:203], v[110:113]
	v_mfma_f32_16x16x32_bf16 v[106:109], v[156:159], v[200:203], v[106:109]
	v_mfma_f32_16x16x32_bf16 v[94:97], v[148:151], v[208:211], v[94:97]
	v_mfma_f32_16x16x32_bf16 v[90:93], v[156:159], v[208:211], v[90:93]
	v_mfma_f32_16x16x32_bf16 v[78:81], v[148:151], v[216:219], v[78:81]
	v_mfma_f32_16x16x32_bf16 v[74:77], v[156:159], v[216:219], v[74:77]
	v_mfma_f32_16x16x32_bf16 v[122:125], v[152:155], v[184:187], v[122:125]
	v_mfma_f32_16x16x32_bf16 v[126:129], v[160:163], v[184:187], v[126:129]
	v_mfma_f32_16x16x32_bf16 v[110:113], v[152:155], v[204:207], v[110:113]
	v_mfma_f32_16x16x32_bf16 v[106:109], v[160:163], v[204:207], v[106:109]
	v_mfma_f32_16x16x32_bf16 v[94:97], v[152:155], v[212:215], v[94:97]
	v_mfma_f32_16x16x32_bf16 v[90:93], v[160:163], v[212:215], v[90:93]
	v_mfma_f32_16x16x32_bf16 v[78:81], v[152:155], v[220:223], v[78:81]
	v_mfma_f32_16x16x32_bf16 v[74:77], v[160:163], v[220:223], v[74:77]
	s_setprio 0
	s_setprio 1
	v_mfma_f32_16x16x32_bf16 v[118:121], v[164:167], v[180:183], v[118:121]
	v_mfma_f32_16x16x32_bf16 v[114:117], v[172:175], v[180:183], v[114:117]
	v_mfma_f32_16x16x32_bf16 v[102:105], v[164:167], v[200:203], v[102:105]
	v_mfma_f32_16x16x32_bf16 v[98:101], v[172:175], v[200:203], v[98:101]
	v_mfma_f32_16x16x32_bf16 v[86:89], v[164:167], v[208:211], v[86:89]
	v_mfma_f32_16x16x32_bf16 v[82:85], v[172:175], v[208:211], v[82:85]
	v_mfma_f32_16x16x32_bf16 v[70:73], v[164:167], v[216:219], v[70:73]
	v_mfma_f32_16x16x32_bf16 v[66:69], v[172:175], v[216:219], v[66:69]
	v_mfma_f32_16x16x32_bf16 v[118:121], v[168:171], v[184:187], v[118:121]
	v_mfma_f32_16x16x32_bf16 v[114:117], v[176:179], v[184:187], v[114:117]
	v_mfma_f32_16x16x32_bf16 v[102:105], v[168:171], v[204:207], v[102:105]
	v_mfma_f32_16x16x32_bf16 v[98:101], v[176:179], v[204:207], v[98:101]
	v_mfma_f32_16x16x32_bf16 v[86:89], v[168:171], v[212:215], v[86:89]
	v_mfma_f32_16x16x32_bf16 v[82:85], v[176:179], v[212:215], v[82:85]
	v_mfma_f32_16x16x32_bf16 v[70:73], v[168:171], v[220:223], v[70:73]
	v_mfma_f32_16x16x32_bf16 v[66:69], v[176:179], v[220:223], v[66:69]
	s_setprio 0
	s_barrier
	s_add_i32 s58, s74, s5
	v_lshl_add_u64 v[142:143], v[142:143], 0, s[24:25]
	s_mov_b32 m0, s58
	ds_read_b128 v[180:183], v147 offset:49152
	ds_read_b128 v[184:187], v147 offset:50176
	ds_read_b128 v[200:203], v147 offset:51200
	ds_read_b128 v[204:207], v147 offset:52224
	ds_read_b128 v[208:211], v147 offset:53248
	ds_read_b128 v[212:215], v147 offset:54272
	ds_read_b128 v[216:219], v147 offset:55296
	ds_read_b128 v[220:223], v147 offset:56320
	global_load_lds_dwordx4 v[142:143], off sc0
	v_lshl_add_u64 v[142:143], v[188:189], 0, s[24:25]
	s_add_i32 m0, s58, 0x2000
	s_add_i32 s58, s75, s5
	global_load_lds_dwordx4 v[142:143], off sc0
	v_lshl_add_u64 v[142:143], v[224:225], 0, s[24:25]
	s_mov_b32 m0, s58
	s_nop 0
	global_load_lds_dwordx4 v[142:143], off sc0
	v_lshl_add_u64 v[142:143], v[226:227], 0, s[24:25]
	s_add_i32 m0, s58, 0x2000
	s_nop 0
	global_load_lds_dwordx4 v[142:143], off sc0
	s_waitcnt vmcnt(6)
	s_waitcnt lgkmcnt(0)
	s_barrier
	s_setprio 1
	s_waitcnt lgkmcnt(0)
	v_mfma_f32_16x16x32_bf16 v[62:65], v[148:151], v[180:183], v[62:65]
	v_mfma_f32_16x16x32_bf16 v[58:61], v[156:159], v[180:183], v[58:61]
	v_mfma_f32_16x16x32_bf16 v[46:49], v[148:151], v[200:203], v[46:49]
	v_mfma_f32_16x16x32_bf16 v[42:45], v[156:159], v[200:203], v[42:45]
	v_mfma_f32_16x16x32_bf16 v[30:33], v[148:151], v[208:211], v[30:33]
	v_mfma_f32_16x16x32_bf16 v[26:29], v[156:159], v[208:211], v[26:29]
	v_mfma_f32_16x16x32_bf16 v[14:17], v[148:151], v[216:219], v[14:17]
	v_mfma_f32_16x16x32_bf16 v[10:13], v[156:159], v[216:219], v[10:13]
	v_mfma_f32_16x16x32_bf16 v[62:65], v[152:155], v[184:187], v[62:65]
	v_mfma_f32_16x16x32_bf16 v[58:61], v[160:163], v[184:187], v[58:61]
	v_mfma_f32_16x16x32_bf16 v[46:49], v[152:155], v[204:207], v[46:49]
	v_mfma_f32_16x16x32_bf16 v[42:45], v[160:163], v[204:207], v[42:45]
	v_mfma_f32_16x16x32_bf16 v[30:33], v[152:155], v[212:215], v[30:33]
	v_mfma_f32_16x16x32_bf16 v[26:29], v[160:163], v[212:215], v[26:29]
	v_mfma_f32_16x16x32_bf16 v[14:17], v[152:155], v[220:223], v[14:17]
	v_mfma_f32_16x16x32_bf16 v[10:13], v[160:163], v[220:223], v[10:13]
	s_setprio 0
	s_setprio 1
	v_mfma_f32_16x16x32_bf16 v[54:57], v[164:167], v[180:183], v[54:57]
	v_mfma_f32_16x16x32_bf16 v[50:53], v[172:175], v[180:183], v[50:53]
	v_mfma_f32_16x16x32_bf16 v[38:41], v[164:167], v[200:203], v[38:41]
	v_mfma_f32_16x16x32_bf16 v[34:37], v[172:175], v[200:203], v[34:37]
	v_mfma_f32_16x16x32_bf16 v[22:25], v[164:167], v[208:211], v[22:25]
	v_mfma_f32_16x16x32_bf16 v[18:21], v[172:175], v[208:211], v[18:21]
	v_mfma_f32_16x16x32_bf16 v[6:9], v[164:167], v[216:219], v[6:9]
	v_mfma_f32_16x16x32_bf16 v[2:5], v[172:175], v[216:219], v[2:5]
	v_mfma_f32_16x16x32_bf16 v[54:57], v[168:171], v[184:187], v[54:57]
	v_mfma_f32_16x16x32_bf16 v[50:53], v[176:179], v[184:187], v[50:53]
	v_mfma_f32_16x16x32_bf16 v[38:41], v[168:171], v[204:207], v[38:41]
	v_mfma_f32_16x16x32_bf16 v[34:37], v[176:179], v[204:207], v[34:37]
	v_mfma_f32_16x16x32_bf16 v[22:25], v[168:171], v[212:215], v[22:25]
	v_mfma_f32_16x16x32_bf16 v[18:21], v[176:179], v[212:215], v[18:21]
	v_mfma_f32_16x16x32_bf16 v[6:9], v[168:171], v[220:223], v[6:9]
	v_mfma_f32_16x16x32_bf16 v[2:5], v[176:179], v[220:223], v[2:5]
	s_setprio 0
	s_barrier
	s_add_u32 s56, s56, 0x100
	s_addc_u32 s57, s57, 0
	s_add_u32 s67, s67, 0x100
	s_addc_u32 s72, s72, 0
	s_cmp_ge_i32 s73, s60
	s_mov_b32 s58, s73
	s_cbranch_scc0 .LBB0_211
	v_readlane_b32 s74, v236, 30
	v_readlane_b32 s75, v236, 31
	v_readlane_b32 s73, v236, 32
	s_mov_b32 s78, s76
